# GEMM prologue de-serialised: K-tile-1 staging issued together with K-tile-0 (first wait vmcnt 8), on top of nomidprio
# baseline (speedup 1.0000x reference)
.LBB0_542:
	v_bfe_u32 v158, v11, 4, 2
	v_and_b32_e32 v131, 15, v11
	v_lshlrev_b32_e32 v17, 4, v158
	v_lshlrev_b32_e32 v11, 2, v11
	s_lshl_b32 s62, s31, 6
	v_lshl_or_b32 v17, v131, 6, v17
	s_lshl_b32 s31, s31, 13
	v_and_b32_e32 v11, 32, v11
	v_bitop3_b32 v18, v17, s31, v11 bitop3:0xde
	s_lshl_b32 s31, s34, 5
	s_and_b32 s63, s31, 0x60
	s_lshl_b32 s31, s63, 7
	s_add_u32 s28, s28, 0x37200000
	s_addc_u32 s29, s29, 0
	s_add_i32 m0, s58, 0x18000
	v_lshl_add_u64 v[8:9], v[8:9], 0, s[16:17]
	global_load_lds_dwordx4 v[8:9], off
	v_lshl_add_u64 v[6:7], v[6:7], 0, s[16:17]
	s_add_i32 m0, s58, 0x1a000
	s_add_i32 s64, s58, 0x8000
	s_add_i32 s69, s58, 0xa000
	global_load_lds_dwordx4 v[6:7], off
	v_lshl_add_u64 v[2:3], v[2:3], 0, s[16:17]
	s_mov_b32 m0, s64
	s_add_u32 s34, s54, 0x80080
	global_load_lds_dwordx4 v[2:3], off
	v_lshl_add_u64 v[2:3], v[4:5], 0, s[16:17]
	s_mov_b32 m0, s69
	s_addc_u32 s35, s55, 0
	global_load_lds_dwordx4 v[2:3], off
	s_add_i32 m0, s58, 0x1c000
	v_lshl_add_u64 v[2:3], s[34:35], 0, v[134:135]
	global_load_lds_dwordx4 v[2:3], off
	v_lshl_add_u64 v[2:3], s[34:35], 0, v[138:139]
	s_add_i32 m0, s58, 0x1e000
	s_cmpk_lt_u32 s30, 0x100
	global_load_lds_dwordx4 v[2:3], off
	s_waitcnt vmcnt(8)
	s_barrier
	v_lshlrev_b32_e32 v2, 15, v10
	v_and_b32_e32 v2, 0xffff0000, v2
	v_lshl_add_u32 v2, v12, 12, v2
	v_and_b32_e32 v3, 1, v10
	v_lshl_or_b32 v2, v3, 6, v2
	v_lshl_add_u32 v140, v13, 1, v2
	v_lshlrev_b32_e32 v2, 15, v14
	v_and_b32_e32 v2, 0xffff0000, v2
	s_waitcnt vmcnt(6)
	v_lshl_add_u32 v2, v15, 12, v2
	v_and_b32_e32 v3, 1, v14
	v_lshl_or_b32 v2, v3, 6, v2
	v_bitop3_b32 v159, v17, s31, v11 bitop3:0xde
	s_cselect_b64 s[30:31], -1, 0
	s_ashr_i32 s70, s7, 31
	v_mov_b32_e32 v141, v181
	v_lshl_add_u32 v142, v16, 1, v2
	v_mov_b32_e32 v143, v181
	s_mov_b32 s71, 0
	v_add_u32_e32 v160, 0, v18
	s_barrier
	s_branch .LBB0_545

.LBB0_815:
	s_add_u32 s22, s22, 0x39600000
	s_addc_u32 s23, s23, 0
	s_add_i32 m0, s45, 0x18000
	v_lshl_add_u64 v[2:3], v[2:3], 0, s[16:17]
	global_load_lds_dwordx4 v[2:3], off
	v_lshl_add_u64 v[2:3], v[4:5], 0, s[16:17]
	s_add_i32 m0, s45, 0x1a000
	s_add_i32 s49, s45, 0x8000
	global_load_lds_dwordx4 v[2:3], off
	v_lshl_add_u64 v[2:3], v[10:11], 0, s[16:17]
	s_mov_b32 m0, s49
	s_add_i32 s50, s45, 0xa000
	global_load_lds_dwordx4 v[2:3], off
	v_lshl_add_u64 v[2:3], v[12:13], 0, s[16:17]
	s_mov_b32 m0, s50
	v_bfe_u32 v144, v14, 4, 2
	global_load_lds_dwordx4 v[2:3], off
	s_add_i32 m0, s45, 0x1c000
	v_lshl_add_u64 v[2:3], v[6:7], 0, s[16:17]
	global_load_lds_dwordx4 v[2:3], off
	v_lshl_add_u64 v[2:3], v[8:9], 0, s[16:17]
	s_add_i32 m0, s45, 0x1e000
	s_lshr_b32 s25, s25, 26
	global_load_lds_dwordx4 v[2:3], off
	s_waitcnt vmcnt(8)
	s_barrier
	v_and_b32_e32 v145, 15, v14
	s_add_i32 s25, s24, s25
	v_lshlrev_b32_e32 v2, 4, v144
	v_lshlrev_b32_e32 v3, 2, v14
	s_ashr_i32 s51, s25, 6
	v_lshl_or_b32 v2, v145, 6, v2
	s_lshl_b32 s25, s28, 13
	v_and_b32_e32 v3, 32, v3
	v_bitop3_b32 v4, v2, s25, v3 bitop3:0xde
	s_lshl_b32 s25, s27, 5
	s_and_b32 s56, s25, 0x60
	s_lshl_b32 s55, s28, 6
	s_lshl_b32 s25, s56, 7
	v_bitop3_b32 v146, v2, s25, v3 bitop3:0xde
	s_cmp_gt_i32 s24, 63
	v_add_u32_e32 v2, v20, v18
	s_waitcnt vmcnt(6)
	s_cselect_b64 s[24:25], -1, 0
	s_add_i32 s57, s51, -2
	v_add_lshl_u32 v180, v2, v19, 1
	v_add_u32_e32 v2, v17, v15
	s_cmpk_lt_u32 s26, 0x100
	v_lshl_add_u64 v[140:141], s[10:11], 0, v[180:181]
	v_add_lshl_u32 v180, v2, v16, 1
	s_cselect_b64 s[26:27], -1, 0
	v_lshl_add_u64 v[142:143], s[10:11], 0, v[180:181]
	s_mov_b32 s58, 0
	v_add_u32_e32 v147, 0, v4
	s_mov_b32 s61, s6
	s_mov_b64 s[28:29], s[34:35]
	s_barrier
	s_branch .LBB0_818

.LBB0_923:
	s_sext_i32_i8 s57, s12
	v_readlane_b32 s12, v255, 41
	s_mulk_i32 s12, 0x600
	s_lshl_b64 s[28:29], s[12:13], 2
	s_add_u32 s18, s18, s28
	s_addc_u32 s19, s19, s29
	v_bfe_u32 v149, v15, 4, 2
	s_add_u32 s22, s22, 0x24600000
	v_and_b32_e32 v148, 15, v15
	v_lshlrev_b32_e32 v19, 4, v149
	v_lshlrev_b32_e32 v15, 2, v15
	s_addc_u32 s23, s23, 0
	s_lshl_b32 s12, s25, 6
	v_lshl_or_b32 v19, v148, 6, v19
	s_lshl_b32 s25, s25, 13
	v_and_b32_e32 v15, 32, v15
	v_bitop3_b32 v20, v19, s25, v15 bitop3:0xde
	s_lshl_b32 s25, s26, 5
	s_and_b32 s48, s25, 0x60
	s_add_i32 m0, s44, 0x18000
	v_lshl_add_u64 v[8:9], v[8:9], 0, s[16:17]
	s_lshl_b32 s25, s48, 7
	global_load_lds_dwordx4 v[8:9], off
	v_lshl_add_u64 v[6:7], v[6:7], 0, s[16:17]
	s_add_i32 m0, s44, 0x1a000
	s_add_i32 s49, s44, 0x8000
	s_add_i32 s50, s44, 0xa000
	global_load_lds_dwordx4 v[6:7], off
	v_lshl_add_u64 v[2:3], v[2:3], 0, s[16:17]
	s_mov_b32 m0, s49
	s_add_u32 s26, s34, 0x60080
	global_load_lds_dwordx4 v[2:3], off
	v_lshl_add_u64 v[2:3], v[4:5], 0, s[16:17]
	s_mov_b32 m0, s50
	s_addc_u32 s27, s35, 0
	global_load_lds_dwordx4 v[2:3], off
	s_add_i32 m0, s44, 0x1c000
	v_lshl_add_u64 v[2:3], s[26:27], 0, v[180:181]
	global_load_lds_dwordx4 v[2:3], off
	v_lshl_add_u64 v[2:3], s[26:27], 0, v[134:135]
	s_add_i32 m0, s44, 0x1e000
	s_movk_i32 s29, 0x600
	global_load_lds_dwordx4 v[2:3], off
	s_waitcnt vmcnt(8)
	s_barrier
	v_lshrrev_b32_e32 v3, 1, v10
	v_mul_lo_u32 v2, v12, s29
	s_movk_i32 s28, 0x6000
	v_mad_u64_u32 v[2:3], s[26:27], v3, s28, v[2:3]
	v_or_b32_e32 v2, v2, v11
	v_add_lshl_u32 v2, v2, v13, 1
	v_mov_b32_e32 v3, v181
	s_mov_b64 s[36:37], 0x60080
	v_lshl_add_u64 v[136:137], v[2:3], 0, s[36:37]
	v_lshrrev_b32_e32 v3, 1, v14
	v_mul_lo_u32 v2, v17, s29
	v_mad_u64_u32 v[2:3], s[26:27], v3, s28, v[2:3]
	s_waitcnt vmcnt(6)
	v_or_b32_e32 v2, v2, v16
	s_cmpk_lt_u32 s24, 0x100
	v_add_lshl_u32 v2, v2, v18, 1
	v_mov_b32_e32 v3, v181
	v_bitop3_b32 v150, v19, s25, v15 bitop3:0xde
	s_cselect_b64 s[24:25], -1, 0
	v_lshl_add_u64 v[138:139], v[2:3], 0, s[36:37]
	s_mov_b32 s51, 0
	v_add_u32_e32 v151, 0, v20
	s_barrier
	s_branch .LBB0_926

.LBB0_1008:
	v_readlane_b32 s3, v255, 43
	s_mul_i32 s18, s3, 0x4200
	s_mov_b32 s19, s13
	s_lshl_b64 s[18:19], s[18:19], 3
	s_add_u32 s18, s30, s18
	s_addc_u32 s19, s31, s19
	s_add_u32 s18, s18, 0x10000
	s_addc_u32 s19, s19, 0
	s_add_u32 s22, s30, 0x20b00000
	s_addc_u32 s23, s31, 0
	s_add_u32 s24, s30, 0x22400000
	s_addc_u32 s25, s31, 0
	v_readlane_b32 s3, v255, 41
	s_add_u32 s26, s30, 0x23d00000
	s_mul_i32 s28, s3, 0x10800
	s_addc_u32 s27, s31, 0
	s_mul_hi_u32 s11, s3, 0x10800
	s_add_u32 s28, s30, s28
	s_addc_u32 s11, s31, s11
	s_add_u32 s28, s28, 0xb0000
	s_addc_u32 s29, s11, 0
	s_lshl_b64 s[44:45], s[12:13], 2
	s_add_u32 s11, s30, s44
	s_addc_u32 s31, s31, s45
	s_add_u32 s30, s11, 0xb000
	s_addc_u32 s31, s31, 0
	s_lshl_b32 s70, s35, 6
	s_lshl_b32 s11, s35, 13
	s_lshl_b32 s35, s42, 5
	s_and_b32 s71, s35, 0x60
	s_add_i32 m0, s61, 0x18000
	v_lshl_add_u64 v[8:9], v[8:9], 0, s[16:17]
	s_lshl_b32 s35, s71, 7
	global_load_lds_dwordx4 v[8:9], off
	v_lshl_add_u64 v[6:7], v[6:7], 0, s[16:17]
	s_add_i32 m0, s61, 0x1a000
	s_add_i32 s74, s61, 0x8000
	s_add_i32 s75, s61, 0xa000
	global_load_lds_dwordx4 v[6:7], off
	v_lshl_add_u64 v[2:3], v[2:3], 0, s[16:17]
	s_mov_b32 m0, s74
	s_add_u32 s42, s40, 0x80080
	global_load_lds_dwordx4 v[2:3], off
	v_lshl_add_u64 v[2:3], v[4:5], 0, s[16:17]
	s_mov_b32 m0, s75
	s_addc_u32 s43, s41, 0
	global_load_lds_dwordx4 v[2:3], off
	s_add_i32 m0, s61, 0x1c000
	v_lshl_add_u64 v[2:3], s[42:43], 0, v[180:181]
	global_load_lds_dwordx4 v[2:3], off
	v_lshl_add_u64 v[2:3], s[42:43], 0, v[136:137]
	s_add_i32 m0, s61, 0x1e000
	v_bfe_u32 v158, v10, 4, 2
	global_load_lds_dwordx4 v[2:3], off
	s_waitcnt vmcnt(8)
	s_barrier
	v_and_b32_e32 v131, 15, v10
	v_lshlrev_b32_e32 v2, 4, v158
	v_lshlrev_b32_e32 v3, 2, v10
	v_lshl_or_b32 v2, v131, 6, v2
	v_and_b32_e32 v3, 32, v3
	v_bitop3_b32 v4, v2, s11, v3 bitop3:0xde
	v_bitop3_b32 v159, v2, s35, v3 bitop3:0xde
	v_lshlrev_b32_e32 v2, 15, v11
	v_and_b32_e32 v2, 0xffff0000, v2
	v_lshl_add_u32 v2, v12, 12, v2
	v_and_b32_e32 v3, 1, v11
	v_lshl_or_b32 v2, v3, 6, v2
	v_lshl_add_u32 v138, v13, 1, v2
	v_lshlrev_b32_e32 v2, 15, v14
	v_and_b32_e32 v2, 0xffff0000, v2
	s_waitcnt vmcnt(6)
	v_lshl_add_u32 v2, v15, 12, v2
	v_and_b32_e32 v3, 1, v14
	s_cmpk_lt_u32 s34, 0x100
	v_lshl_or_b32 v2, v3, 6, v2
	s_cselect_b64 s[34:35], -1, 0
	s_ashr_i32 s76, s6, 31
	v_mov_b32_e32 v139, v181
	v_lshl_add_u32 v140, v16, 1, v2
	v_mov_b32_e32 v141, v181
	s_mov_b32 s82, 0
	v_add_u32_e32 v160, 0, v4
	s_barrier
	s_branch .LBB0_1011

.LBB0_1226:
	s_add_u32 s26, s28, 0xe0000
	s_addc_u32 s27, s29, 0
	s_add_u32 s28, s28, 0x20300000
	s_addc_u32 s29, s29, 0
	v_bfe_u32 v152, v16, 4, 2
	s_lshl_b32 s31, s31, 5
	v_and_b32_e32 v131, 15, v16
	v_lshlrev_b32_e32 v17, 4, v152
	v_lshlrev_b32_e32 v16, 2, v16
	s_and_b32 s49, s31, 0x60
	s_add_i32 m0, s11, 0x18000
	v_lshl_add_u64 v[8:9], v[8:9], 0, s[16:17]
	s_lshl_b32 s48, s34, 6
	v_lshl_or_b32 v17, v131, 6, v17
	s_lshl_b32 s34, s34, 13
	v_and_b32_e32 v16, 32, v16
	s_lshl_b32 s31, s49, 7
	global_load_lds_dwordx4 v[8:9], off
	v_lshl_add_u64 v[6:7], v[6:7], 0, s[16:17]
	s_add_i32 m0, s11, 0x1a000
	s_add_i32 s50, s11, 0x8000
	s_add_i32 s51, s11, 0xa000
	v_bitop3_b32 v18, v17, s34, v16 bitop3:0xde
	global_load_lds_dwordx4 v[6:7], off
	v_lshl_add_u64 v[2:3], v[2:3], 0, s[16:17]
	s_mov_b32 m0, s50
	s_add_u32 s34, s14, 0x80080
	global_load_lds_dwordx4 v[2:3], off
	v_lshl_add_u64 v[2:3], v[4:5], 0, s[16:17]
	s_mov_b32 m0, s51
	s_addc_u32 s35, s15, 0
	global_load_lds_dwordx4 v[2:3], off
	s_add_i32 m0, s11, 0x1c000
	v_lshl_add_u64 v[2:3], s[34:35], 0, v[134:135]
	global_load_lds_dwordx4 v[2:3], off
	v_lshl_add_u64 v[2:3], s[34:35], 0, v[132:133]
	s_add_i32 m0, s11, 0x1e000
	s_cmpk_lt_u32 s30, 0x100
	global_load_lds_dwordx4 v[2:3], off
	s_waitcnt vmcnt(8)
	s_barrier
	v_lshlrev_b32_e32 v2, 15, v13
	v_and_b32_e32 v2, 0xffff0000, v2
	v_lshl_add_u32 v2, v14, 12, v2
	v_and_b32_e32 v3, 1, v13
	v_lshl_or_b32 v2, v3, 6, v2
	v_lshl_add_u32 v136, v15, 1, v2
	v_lshlrev_b32_e32 v2, 15, v10
	v_and_b32_e32 v2, 0xffff0000, v2
	s_waitcnt vmcnt(6)
	v_lshl_add_u32 v2, v11, 12, v2
	v_and_b32_e32 v3, 1, v10
	v_lshl_or_b32 v2, v3, 6, v2
	v_bitop3_b32 v153, v17, s31, v16 bitop3:0xde
	s_cselect_b64 s[30:31], -1, 0
	v_mov_b32_e32 v137, v181
	v_lshl_add_u32 v138, v12, 1, v2
	v_mov_b32_e32 v139, v181
	s_mov_b32 s54, 0
	v_add_u32_e32 v154, 0, v18
	s_barrier
	s_branch .LBB0_1229

.LBB0_1573:
	s_waitcnt vmcnt(0)
	v_lshlrev_b32_e32 v90, 16, v48
	v_and_b32_e32 v91, 0xffff0000, v48
	v_lshlrev_b32_e32 v92, 16, v49
	v_and_b32_e32 v93, 0xffff0000, v49
	v_lshlrev_b32_e32 v94, 16, v46
	v_and_b32_e32 v95, 0xffff0000, v46
	v_lshlrev_b32_e32 v96, 16, v47
	v_and_b32_e32 v97, 0xffff0000, v47
	v_lshlrev_b32_e32 v46, 16, v28
	v_and_b32_e32 v47, 0xffff0000, v28
	v_lshlrev_b32_e32 v48, 16, v29
	v_and_b32_e32 v49, 0xffff0000, v29
	s_add_i32 m0, s56, 0x18000
	v_lshl_add_u64 v[28:29], v[144:145], 0, s[16:17]
	s_lshl_b32 s31, s28, 13
	s_lshl_b32 s34, s21, 7
	global_load_lds_dwordx4 v[28:29], off
	v_lshl_add_u64 v[28:29], v[142:143], 0, s[16:17]
	s_add_i32 m0, s56, 0x1a000
	s_add_i32 s60, s56, 0x8000
	s_add_i32 s61, s56, 0xa000
	global_load_lds_dwordx4 v[28:29], off
	v_lshl_add_u64 v[28:29], v[68:69], 0, s[16:17]
	s_mov_b32 m0, s60
	s_add_u32 s28, s46, 0x80080
	global_load_lds_dwordx4 v[28:29], off
	v_lshl_add_u64 v[28:29], v[140:141], 0, s[16:17]
	s_mov_b32 m0, s61
	s_addc_u32 s29, s47, 0
	global_load_lds_dwordx4 v[28:29], off
	s_add_i32 m0, s56, 0x1c000
	v_lshl_add_u64 v[28:29], s[28:29], 0, v[134:135]
	global_load_lds_dwordx4 v[28:29], off
	v_lshl_add_u64 v[28:29], s[28:29], 0, v[138:139]
	s_add_i32 m0, s56, 0x1e000
	v_or_b32_e32 v151, s9, v150
	global_load_lds_dwordx4 v[28:29], off
	s_waitcnt vmcnt(8)
	s_barrier
	v_lshlrev_b32_e32 v140, 6, v151
	s_movk_i32 s28, 0x3c0
	v_lshlrev_b32_e32 v141, 2, v151
	v_and_or_b32 v140, v140, s28, v180
	v_and_b32_e32 v141, 32, v141
	v_bitop3_b32 v144, v140, s31, v141 bitop3:0xde
	v_lshlrev_b32_e32 v141, 2, v150
	v_lshl_or_b32 v140, v150, 6, v180
	v_and_b32_e32 v141, 32, v141
	v_bitop3_b32 v152, v140, s34, v141 bitop3:0xde
	v_lshlrev_b32_e32 v140, 15, v146
	v_lshlrev_b32_e32 v142, 15, v154
	v_and_b32_e32 v140, 0xffff0000, v140
	v_and_b32_e32 v142, 0xffff0000, v142
	s_waitcnt vmcnt(6)
	v_lshl_add_u32 v140, v147, 12, v140
	v_and_b32_e32 v141, 1, v146
	v_lshl_add_u32 v142, v155, 12, v142
	v_and_b32_e32 v143, 1, v154
	v_lshlrev_b32_e32 v157, 3, v131
	s_cmpk_lt_u32 s30, 0x100
	v_lshl_or_b32 v140, v141, 6, v140
	v_lshl_or_b32 v142, v143, 6, v142
	v_lshlrev_b32_e32 v126, 16, v64
	v_and_b32_e32 v127, 0xffff0000, v64
	v_lshlrev_b32_e32 v128, 16, v65
	v_and_b32_e32 v129, 0xffff0000, v65
	v_lshlrev_b32_e32 v114, 16, v66
	v_and_b32_e32 v115, 0xffff0000, v66
	v_lshlrev_b32_e32 v116, 16, v67
	v_and_b32_e32 v117, 0xffff0000, v67
	v_lshlrev_b32_e32 v118, 16, v60
	v_and_b32_e32 v119, 0xffff0000, v60
	v_lshlrev_b32_e32 v120, 16, v61
	v_and_b32_e32 v121, 0xffff0000, v61
	v_lshlrev_b32_e32 v122, 16, v62
	v_and_b32_e32 v123, 0xffff0000, v62
	v_lshlrev_b32_e32 v124, 16, v63
	v_and_b32_e32 v125, 0xffff0000, v63
	v_lshlrev_b32_e32 v106, 16, v56
	v_and_b32_e32 v107, 0xffff0000, v56
	v_lshlrev_b32_e32 v108, 16, v57
	v_and_b32_e32 v109, 0xffff0000, v57
	v_lshlrev_b32_e32 v98, 16, v58
	v_and_b32_e32 v99, 0xffff0000, v58
	v_lshlrev_b32_e32 v100, 16, v59
	v_and_b32_e32 v101, 0xffff0000, v59
	v_lshlrev_b32_e32 v102, 16, v52
	v_and_b32_e32 v103, 0xffff0000, v52
	v_lshlrev_b32_e32 v104, 16, v53
	v_and_b32_e32 v105, 0xffff0000, v53
	v_lshlrev_b32_e32 v110, 16, v54
	v_and_b32_e32 v111, 0xffff0000, v54
	v_lshlrev_b32_e32 v112, 16, v55
	v_and_b32_e32 v113, 0xffff0000, v55
	v_lshlrev_b32_e32 v82, 16, v50
	v_and_b32_e32 v83, 0xffff0000, v50
	v_lshlrev_b32_e32 v84, 16, v51
	v_and_b32_e32 v85, 0xffff0000, v51
	v_lshlrev_b32_e32 v86, 16, v44
	v_and_b32_e32 v87, 0xffff0000, v44
	v_lshlrev_b32_e32 v88, 16, v45
	v_and_b32_e32 v89, 0xffff0000, v45
	v_lshlrev_b32_e32 v74, 16, v40
	v_and_b32_e32 v75, 0xffff0000, v40
	v_lshlrev_b32_e32 v76, 16, v41
	v_and_b32_e32 v77, 0xffff0000, v41
	v_lshlrev_b32_e32 v54, 16, v42
	v_and_b32_e32 v55, 0xffff0000, v42
	v_lshlrev_b32_e32 v56, 16, v43
	v_and_b32_e32 v57, 0xffff0000, v43
	v_lshlrev_b32_e32 v70, 16, v36
	v_and_b32_e32 v71, 0xffff0000, v36
	v_lshlrev_b32_e32 v72, 16, v37
	v_and_b32_e32 v73, 0xffff0000, v37
	v_lshlrev_b32_e32 v78, 16, v38
	v_and_b32_e32 v79, 0xffff0000, v38
	v_lshlrev_b32_e32 v80, 16, v39
	v_and_b32_e32 v81, 0xffff0000, v39
	v_lshlrev_b32_e32 v50, 16, v32
	v_and_b32_e32 v51, 0xffff0000, v32
	v_lshlrev_b32_e32 v52, 16, v33
	v_and_b32_e32 v53, 0xffff0000, v33
	v_lshlrev_b32_e32 v38, 16, v34
	v_and_b32_e32 v39, 0xffff0000, v34
	v_lshlrev_b32_e32 v40, 16, v35
	v_and_b32_e32 v41, 0xffff0000, v35
	v_lshlrev_b32_e32 v58, 16, v30
	v_and_b32_e32 v59, 0xffff0000, v30
	v_lshlrev_b32_e32 v60, 16, v31
	v_and_b32_e32 v61, 0xffff0000, v31
	v_lshlrev_b32_e32 v22, 16, v24
	v_and_b32_e32 v23, 0xffff0000, v24
	v_lshlrev_b32_e32 v24, 16, v25
	v_and_b32_e32 v25, 0xffff0000, v25
	v_lshlrev_b32_e32 v42, 16, v26
	v_and_b32_e32 v43, 0xffff0000, v26
	v_lshlrev_b32_e32 v44, 16, v27
	v_and_b32_e32 v45, 0xffff0000, v27
	v_lshlrev_b32_e32 v62, 16, v18
	v_and_b32_e32 v63, 0xffff0000, v18
	v_lshlrev_b32_e32 v64, 16, v19
	v_and_b32_e32 v65, 0xffff0000, v19
	v_lshlrev_b32_e32 v66, 16, v20
	v_and_b32_e32 v67, 0xffff0000, v20
	v_lshlrev_b32_e32 v68, 16, v21
	v_and_b32_e32 v69, 0xffff0000, v21
	v_lshlrev_b32_e32 v30, 16, v10
	v_and_b32_e32 v31, 0xffff0000, v10
	v_lshlrev_b32_e32 v32, 16, v11
	v_and_b32_e32 v33, 0xffff0000, v11
	v_lshlrev_b32_e32 v18, 16, v12
	v_and_b32_e32 v19, 0xffff0000, v12
	v_lshlrev_b32_e32 v20, 16, v13
	v_and_b32_e32 v21, 0xffff0000, v13
	v_lshlrev_b32_e32 v26, 16, v6
	v_and_b32_e32 v27, 0xffff0000, v6
	v_lshlrev_b32_e32 v28, 16, v7
	v_and_b32_e32 v29, 0xffff0000, v7
	v_lshlrev_b32_e32 v34, 16, v8
	v_and_b32_e32 v35, 0xffff0000, v8
	v_lshlrev_b32_e32 v36, 16, v9
	v_and_b32_e32 v37, 0xffff0000, v9
	v_lshlrev_b32_e32 v10, 16, v2
	v_and_b32_e32 v11, 0xffff0000, v2
	v_lshlrev_b32_e32 v12, 16, v3
	v_and_b32_e32 v13, 0xffff0000, v3
	v_lshlrev_b32_e32 v2, 16, v4
	v_and_b32_e32 v3, 0xffff0000, v4
	v_lshlrev_b32_e32 v4, 16, v5
	v_and_b32_e32 v5, 0xffff0000, v5
	v_lshlrev_b32_e32 v6, 16, v14
	v_and_b32_e32 v7, 0xffff0000, v14
	v_lshlrev_b32_e32 v8, 16, v15
	v_and_b32_e32 v9, 0xffff0000, v15
	v_lshlrev_b32_e32 v14, 16, v16
	v_and_b32_e32 v15, 0xffff0000, v16
	v_lshlrev_b32_e32 v16, 16, v17
	v_and_b32_e32 v17, 0xffff0000, v17
	s_cselect_b64 s[28:29], -1, 0
	s_ashr_i32 s62, s7, 31
	v_lshl_add_u32 v140, v153, 1, v140
	v_mov_b32_e32 v141, v181
	v_lshl_add_u32 v142, v156, 1, v142
	v_mov_b32_e32 v143, v181
	s_mov_b32 s63, 0
	v_add_u32_e32 v153, 0, v144
	v_lshlrev_b32_e32 v180, 1, v157
	s_barrier
	s_branch .LBB0_1576

.LBB0_1675:
	s_lshl_b32 s18, s8, 3
	s_mul_hi_u32 s15, s8, 0x560000
	s_mul_i32 s27, s8, 0x560000
	s_mul_hi_u32 s30, s8, 0x10200
	s_mul_i32 s31, s8, 0x10200
	s_mul_hi_u32 s34, s8, 0x5600
	s_mul_i32 s35, s8, 0x5600
	v_writelane_b32 v255, s18, 44
	s_lshl_b32 s8, s8, 7
	s_lshl_b64 s[18:19], s[12:13], 3
	s_add_u32 s45, s38, s18
	s_addc_u32 s50, s39, s19
	s_add_u32 s58, s38, 0x31900000
	s_addc_u32 s59, s39, 0
	s_waitcnt lgkmcnt(0)
	s_add_u32 s60, s2, s27
	s_addc_u32 s61, s3, s15
	s_add_u32 s27, s40, s31
	s_addc_u32 s40, s41, s30
	s_add_u32 s41, s42, s35
	s_addc_u32 s42, s43, s34
	v_readlane_b32 s2, v255, 53
	s_add_u32 s62, s38, 0x3b000000
	v_readlane_b32 s3, v255, 54
	s_addc_u32 s63, s39, 0
	s_lshl_b64 s[2:3], s[2:3], 2
	s_add_u32 s2, s38, s2
	s_addc_u32 s3, s39, s3
	s_add_u32 s2, s2, 0x8000
	s_addc_u32 s3, s3, 0
	v_writelane_b32 v255, s2, 58
	v_and_b32_e32 v17, 63, v16
	v_and_b32_e32 v191, 15, v16
	v_bfe_u32 v238, v16, 4, 2
	v_and_b32_e32 v18, 48, v16
	v_lshlrev_b32_e32 v16, 2, v16
	v_writelane_b32 v255, s3, 59
	s_lshl_b32 s2, s11, 13
	v_lshl_or_b32 v18, v191, 6, v18
	v_and_b32_e32 v16, 32, v16
	v_bitop3_b32 v19, v18, s2, v16 bitop3:0xde
	s_lshl_b32 s2, s14, 5
	s_and_b32 s35, s2, 0x60
	s_add_i32 m0, s6, 0x18000
	v_lshl_add_u64 v[8:9], v[8:9], 0, s[16:17]
	s_lshl_b32 s34, s11, 6
	s_lshl_b32 s3, s35, 7
	global_load_lds_dwordx4 v[8:9], off
	v_lshl_add_u64 v[6:7], v[6:7], 0, s[16:17]
	s_add_i32 m0, s6, 0x1a000
	s_add_i32 s54, s6, 0x8000
	s_add_i32 s55, s6, 0xa000
	global_load_lds_dwordx4 v[6:7], off
	v_lshl_add_u64 v[2:3], v[2:3], 0, s[16:17]
	s_mov_b32 m0, s54
	s_add_u32 s18, s46, 0x80080
	global_load_lds_dwordx4 v[2:3], off
	v_lshl_add_u64 v[2:3], v[4:5], 0, s[16:17]
	s_mov_b32 m0, s55
	s_addc_u32 s19, s47, 0
	global_load_lds_dwordx4 v[2:3], off
	s_add_i32 m0, s6, 0x1c000
	v_lshl_add_u64 v[2:3], s[18:19], 0, v[180:181]
	global_load_lds_dwordx4 v[2:3], off
	v_lshl_add_u64 v[2:3], s[18:19], 0, v[196:197]
	s_add_i32 m0, s6, 0x1e000
	s_ashr_i32 s18, s10, 7
	global_load_lds_dwordx4 v[2:3], off
	s_waitcnt vmcnt(8)
	s_barrier
	v_bitop3_b32 v239, s3, v18, v16 bitop3:0xf6
	s_lshl_b32 s51, s18, 9
	s_ashr_i32 s3, s2, 31
	s_lshl_b32 s68, s14, 8
	s_cmpk_lt_u32 s10, 0x100
	s_cselect_b64 s[30:31], -1, 0
	s_lshl_b32 s14, s11, 1
	s_add_i32 s14, s14, 0x7ffff2
	s_cmp_gt_i32 s11, 0
	v_writelane_b32 v255, s14, 50
	s_cselect_b64 s[14:15], -1, 0
	s_lshl_b32 s66, s11, 10
	v_writelane_b32 v255, s14, 41
	s_cmpk_gt_u32 s10, 0xff
	s_mul_i32 s43, s18, 0x5600
	v_writelane_b32 v255, s15, 42
	s_cselect_b64 s[14:15], -1, 0
	s_cmp_gt_i32 s11, -1
	s_cselect_b64 s[70:71], -1, 0
	s_ashr_i32 s83, s28, 31
	s_mul_hi_i32 s19, s18, 0x5600
	s_add_u32 s11, s27, s43
	s_addc_u32 s19, s40, s19
	s_cmp_lt_i32 s18, 3
	s_cselect_b32 s18, s19, s42
	s_cselect_b32 s11, s11, s41
	s_lshl_b32 s10, s10, 2
	s_and_b32 s19, s10, 0x100
	s_add_u32 s10, s11, s19
	s_addc_u32 s11, s18, 0
	v_lshlrev_b32_e32 v2, 2, v17
	v_mov_b32_e32 v3, v181
	v_writelane_b32 v255, s70, 15
	v_lshl_add_u64 v[198:199], s[10:11], 0, v[2:3]
	s_add_i32 s10, s51, 0
	v_writelane_b32 v255, s71, 16
	s_add_i32 s70, s10, s19
	s_add_i32 s70, s70, 0x21000
	s_lshl_b64 s[2:3], s[2:3], 3
	s_add_u32 s2, s45, s2
	s_addc_u32 s3, s50, s3
	v_lshl_add_u64 v[2:3], s[2:3], 0, v[2:3]
	s_mov_b64 s[2:3], 0x20800
	v_lshl_add_u64 v[200:201], v[2:3], 0, s[2:3]
	s_add_u32 s74, s38, 0x3b300000
	v_lshlrev_b32_e32 v2, 15, v10
	s_addc_u32 s75, s39, 0
	s_add_i32 s2, s66, 0
	v_and_b32_e32 v2, 0xffff0000, v2
	s_add_i32 s2, s2, 0x20000
	v_lshl_add_u32 v2, v11, 12, v2
	v_and_b32_e32 v3, 1, v10
	s_add_u32 s96, s36, 0x5160000
	v_lshl_or_b32 v2, v3, 6, v2
	s_addc_u32 s97, s37, 0
	v_lshl_add_u32 v202, v12, 1, v2
	v_lshlrev_b32_e32 v2, 15, v13
	s_add_u32 s66, s36, 0x5e0c000
	v_and_b32_e32 v2, 0xffff0000, v2
	s_waitcnt vmcnt(6)
	v_writelane_b32 v255, s2, 46
	s_addc_u32 s67, s37, 0
	v_lshl_add_u32 v2, v14, 12, v2
	v_and_b32_e32 v3, 1, v13
	s_xor_b64 s[2:3], s[14:15], -1
	v_lshl_or_b32 v2, v3, 6, v2
	s_add_i32 s71, s68, 0
	v_writelane_b32 v255, s2, 48
	s_mov_b32 s82, 0
	v_mov_b32_e32 v203, v181
	v_lshl_add_u32 v204, v15, 1, v2
	v_mov_b32_e32 v205, v181
	s_add_i32 s71, s71, 0x21800
	v_add_u32_e32 v240, 0, v19
	v_writelane_b32 v255, s3, 49
	s_barrier
	s_branch .LBB0_1678

.LBB0_1757:
	s_add_u32 s28, s26, 0xe0000
	s_addc_u32 s29, s27, 0
	v_bfe_u32 v152, v16, 4, 2
	s_add_u32 s30, s26, 0x20300000
	v_and_b32_e32 v151, 15, v16
	v_lshlrev_b32_e32 v17, 4, v152
	v_lshlrev_b32_e32 v16, 2, v16
	s_addc_u32 s31, s27, 0
	v_lshl_or_b32 v17, v151, 6, v17
	s_lshl_b32 s26, s36, 13
	v_and_b32_e32 v16, 32, v16
	v_bitop3_b32 v18, v17, s26, v16 bitop3:0xde
	s_lshl_b32 s26, s35, 5
	s_and_b32 s49, s26, 0x60
	s_add_i32 m0, s3, 0x18000
	v_lshl_add_u64 v[8:9], v[8:9], 0, s[16:17]
	s_lshl_b32 s48, s36, 6
	s_lshl_b32 s26, s49, 7
	global_load_lds_dwordx4 v[8:9], off
	v_lshl_add_u64 v[6:7], v[6:7], 0, s[16:17]
	s_add_i32 m0, s3, 0x1a000
	s_add_i32 s50, s3, 0x8000
	s_add_i32 s51, s3, 0xa000
	v_bitop3_b32 v153, v17, s26, v16 bitop3:0xde
	global_load_lds_dwordx4 v[6:7], off
	v_lshl_add_u64 v[2:3], v[2:3], 0, s[16:17]
	s_mov_b32 m0, s50
	s_add_u32 s26, s10, 0x80080
	global_load_lds_dwordx4 v[2:3], off
	v_lshl_add_u64 v[2:3], v[4:5], 0, s[16:17]
	s_mov_b32 m0, s51
	s_addc_u32 s27, s11, 0
	global_load_lds_dwordx4 v[2:3], off
	s_add_i32 m0, s3, 0x1c000
	v_lshl_add_u64 v[2:3], s[26:27], 0, v[132:133]
	global_load_lds_dwordx4 v[2:3], off
	v_lshl_add_u64 v[2:3], s[26:27], 0, v[130:131]
	s_add_i32 m0, s3, 0x1e000
	s_cmpk_lt_u32 s34, 0x100
	global_load_lds_dwordx4 v[2:3], off
	s_waitcnt vmcnt(8)
	s_barrier
	v_lshlrev_b32_e32 v2, 15, v13
	v_and_b32_e32 v2, 0xffff0000, v2
	v_lshl_add_u32 v2, v14, 12, v2
	v_and_b32_e32 v3, 1, v13
	v_lshl_or_b32 v2, v3, 6, v2
	v_lshl_add_u32 v134, v15, 1, v2
	v_lshlrev_b32_e32 v2, 15, v10
	v_and_b32_e32 v2, 0xffff0000, v2
	s_waitcnt vmcnt(6)
	v_lshl_add_u32 v2, v11, 12, v2
	v_and_b32_e32 v3, 1, v10
	v_lshl_or_b32 v2, v3, 6, v2
	s_cselect_b64 s[34:35], -1, 0
	v_mov_b32_e32 v135, v181
	v_lshl_add_u32 v136, v12, 1, v2
	v_mov_b32_e32 v137, v181
	s_mov_b32 s54, 0
	v_add_u32_e32 v154, 0, v18
	s_barrier
	s_branch .LBB0_1760

.LBB0_2227:
	s_waitcnt vmcnt(0)
	v_lshlrev_b32_e32 v90, 16, v48
	v_and_b32_e32 v91, 0xffff0000, v48
	v_lshlrev_b32_e32 v92, 16, v49
	v_and_b32_e32 v93, 0xffff0000, v49
	v_lshlrev_b32_e32 v94, 16, v46
	v_and_b32_e32 v95, 0xffff0000, v46
	v_lshlrev_b32_e32 v96, 16, v47
	v_and_b32_e32 v97, 0xffff0000, v47
	v_lshlrev_b32_e32 v46, 16, v28
	v_and_b32_e32 v47, 0xffff0000, v28
	v_lshlrev_b32_e32 v48, 16, v29
	v_and_b32_e32 v49, 0xffff0000, v29
	s_add_i32 m0, s43, 0x18000
	v_lshl_add_u64 v[28:29], v[146:147], 0, s[16:17]
	s_lshl_b32 s23, s18, 13
	s_lshl_b32 s24, s42, 7
	global_load_lds_dwordx4 v[28:29], off
	v_lshl_add_u64 v[28:29], v[144:145], 0, s[16:17]
	s_add_i32 m0, s43, 0x1a000
	s_add_i32 s48, s43, 0x8000
	s_add_i32 s49, s43, 0xa000
	global_load_lds_dwordx4 v[28:29], off
	v_lshl_add_u64 v[28:29], v[68:69], 0, s[16:17]
	s_mov_b32 m0, s48
	s_add_u32 s18, s28, 0x158080
	global_load_lds_dwordx4 v[28:29], off
	v_lshl_add_u64 v[28:29], v[142:143], 0, s[16:17]
	s_mov_b32 m0, s49
	s_addc_u32 s19, s29, 0
	global_load_lds_dwordx4 v[28:29], off
	s_add_i32 m0, s43, 0x1c000
	v_lshl_add_u64 v[28:29], s[18:19], 0, v[136:137]
	global_load_lds_dwordx4 v[28:29], off
	v_lshl_add_u64 v[28:29], s[18:19], 0, v[140:141]
	s_add_i32 m0, s43, 0x1e000
	v_readlane_b32 s18, v255, 43
	global_load_lds_dwordx4 v[28:29], off
	s_waitcnt vmcnt(8)
	s_barrier
	s_mulk_i32 s18, 0x4200
	s_mov_b32 s19, s13
	v_lshl_add_u64 v[142:143], s[18:19], 3, v[130:131]
	s_mov_b64 s[18:19], 0x31000
	v_or_b32_e32 v155, s41, v154
	v_lshl_add_u64 v[142:143], v[142:143], 0, s[18:19]
	v_lshlrev_b32_e32 v144, 6, v155
	s_movk_i32 s18, 0x3c0
	v_lshlrev_b32_e32 v145, 2, v155
	v_and_or_b32 v144, v144, s18, v180
	v_and_b32_e32 v145, 32, v145
	v_bitop3_b32 v162, v144, s23, v145 bitop3:0xde
	v_lshlrev_b32_e32 v145, 2, v154
	v_lshl_or_b32 v144, v154, 6, v180
	v_and_b32_e32 v145, 32, v145
	v_bitop3_b32 v156, v144, s24, v145 bitop3:0xde
	s_movk_i32 s24, 0x1580
	v_lshrrev_b32_e32 v145, 1, v148
	v_mul_lo_u32 v144, v150, s24
	s_mov_b32 s25, 0x15800
	s_cmpk_lt_u32 s22, 0x100
	v_mad_u64_u32 v[144:145], s[22:23], v145, s25, v[144:145]
	v_lshrrev_b32_e32 v147, 1, v157
	v_mul_lo_u32 v146, v159, s24
	v_or_b32_e32 v144, v144, v149
	v_mad_u64_u32 v[146:147], s[22:23], v147, s25, v[146:147]
	s_waitcnt vmcnt(6)
	v_add_lshl_u32 v180, v144, v151, 1
	s_mov_b64 s[30:31], 0x158080
	v_or_b32_e32 v146, v146, v158
	v_lshlrev_b32_e32 v161, 3, v153
	v_lshl_add_u64 v[144:145], v[180:181], 0, s[30:31]
	v_add_lshl_u32 v180, v146, v160, 1
	v_lshlrev_b32_e32 v126, 16, v64
	v_and_b32_e32 v127, 0xffff0000, v64
	v_lshlrev_b32_e32 v128, 16, v65
	v_and_b32_e32 v129, 0xffff0000, v65
	v_lshlrev_b32_e32 v114, 16, v66
	v_and_b32_e32 v115, 0xffff0000, v66
	v_lshlrev_b32_e32 v116, 16, v67
	v_and_b32_e32 v117, 0xffff0000, v67
	v_lshlrev_b32_e32 v118, 16, v60
	v_and_b32_e32 v119, 0xffff0000, v60
	v_lshlrev_b32_e32 v120, 16, v61
	v_and_b32_e32 v121, 0xffff0000, v61
	v_lshlrev_b32_e32 v122, 16, v62
	v_and_b32_e32 v123, 0xffff0000, v62
	v_lshlrev_b32_e32 v124, 16, v63
	v_and_b32_e32 v125, 0xffff0000, v63
	v_lshlrev_b32_e32 v106, 16, v56
	v_and_b32_e32 v107, 0xffff0000, v56
	v_lshlrev_b32_e32 v108, 16, v57
	v_and_b32_e32 v109, 0xffff0000, v57
	v_lshlrev_b32_e32 v98, 16, v58
	v_and_b32_e32 v99, 0xffff0000, v58
	v_lshlrev_b32_e32 v100, 16, v59
	v_and_b32_e32 v101, 0xffff0000, v59
	v_lshlrev_b32_e32 v102, 16, v52
	v_and_b32_e32 v103, 0xffff0000, v52
	v_lshlrev_b32_e32 v104, 16, v53
	v_and_b32_e32 v105, 0xffff0000, v53
	v_lshlrev_b32_e32 v110, 16, v54
	v_and_b32_e32 v111, 0xffff0000, v54
	v_lshlrev_b32_e32 v112, 16, v55
	v_and_b32_e32 v113, 0xffff0000, v55
	v_lshlrev_b32_e32 v82, 16, v50
	v_and_b32_e32 v83, 0xffff0000, v50
	v_lshlrev_b32_e32 v84, 16, v51
	v_and_b32_e32 v85, 0xffff0000, v51
	v_lshlrev_b32_e32 v86, 16, v44
	v_and_b32_e32 v87, 0xffff0000, v44
	v_lshlrev_b32_e32 v88, 16, v45
	v_and_b32_e32 v89, 0xffff0000, v45
	v_lshlrev_b32_e32 v74, 16, v40
	v_and_b32_e32 v75, 0xffff0000, v40
	v_lshlrev_b32_e32 v76, 16, v41
	v_and_b32_e32 v77, 0xffff0000, v41
	v_lshlrev_b32_e32 v54, 16, v42
	v_and_b32_e32 v55, 0xffff0000, v42
	v_lshlrev_b32_e32 v56, 16, v43
	v_and_b32_e32 v57, 0xffff0000, v43
	v_lshlrev_b32_e32 v70, 16, v36
	v_and_b32_e32 v71, 0xffff0000, v36
	v_lshlrev_b32_e32 v72, 16, v37
	v_and_b32_e32 v73, 0xffff0000, v37
	v_lshlrev_b32_e32 v78, 16, v38
	v_and_b32_e32 v79, 0xffff0000, v38
	v_lshlrev_b32_e32 v80, 16, v39
	v_and_b32_e32 v81, 0xffff0000, v39
	v_lshlrev_b32_e32 v50, 16, v32
	v_and_b32_e32 v51, 0xffff0000, v32
	v_lshlrev_b32_e32 v52, 16, v33
	v_and_b32_e32 v53, 0xffff0000, v33
	v_lshlrev_b32_e32 v38, 16, v34
	v_and_b32_e32 v39, 0xffff0000, v34
	v_lshlrev_b32_e32 v40, 16, v35
	v_and_b32_e32 v41, 0xffff0000, v35
	v_lshlrev_b32_e32 v58, 16, v30
	v_and_b32_e32 v59, 0xffff0000, v30
	v_lshlrev_b32_e32 v60, 16, v31
	v_and_b32_e32 v61, 0xffff0000, v31
	v_lshlrev_b32_e32 v22, 16, v24
	v_and_b32_e32 v23, 0xffff0000, v24
	v_lshlrev_b32_e32 v24, 16, v25
	v_and_b32_e32 v25, 0xffff0000, v25
	v_lshlrev_b32_e32 v42, 16, v26
	v_and_b32_e32 v43, 0xffff0000, v26
	v_lshlrev_b32_e32 v44, 16, v27
	v_and_b32_e32 v45, 0xffff0000, v27
	v_lshlrev_b32_e32 v62, 16, v18
	v_and_b32_e32 v63, 0xffff0000, v18
	v_lshlrev_b32_e32 v64, 16, v19
	v_and_b32_e32 v65, 0xffff0000, v19
	v_lshlrev_b32_e32 v66, 16, v20
	v_and_b32_e32 v67, 0xffff0000, v20
	v_lshlrev_b32_e32 v68, 16, v21
	v_and_b32_e32 v69, 0xffff0000, v21
	v_lshlrev_b32_e32 v30, 16, v10
	v_and_b32_e32 v31, 0xffff0000, v10
	v_lshlrev_b32_e32 v32, 16, v11
	v_and_b32_e32 v33, 0xffff0000, v11
	v_lshlrev_b32_e32 v18, 16, v12
	v_and_b32_e32 v19, 0xffff0000, v12
	v_lshlrev_b32_e32 v20, 16, v13
	v_and_b32_e32 v21, 0xffff0000, v13
	v_lshlrev_b32_e32 v26, 16, v6
	v_and_b32_e32 v27, 0xffff0000, v6
	v_lshlrev_b32_e32 v28, 16, v7
	v_and_b32_e32 v29, 0xffff0000, v7
	v_lshlrev_b32_e32 v34, 16, v8
	v_and_b32_e32 v35, 0xffff0000, v8
	v_lshlrev_b32_e32 v36, 16, v9
	v_and_b32_e32 v37, 0xffff0000, v9
	v_lshlrev_b32_e32 v10, 16, v2
	v_and_b32_e32 v11, 0xffff0000, v2
	v_lshlrev_b32_e32 v12, 16, v3
	v_and_b32_e32 v13, 0xffff0000, v3
	v_lshlrev_b32_e32 v2, 16, v4
	v_and_b32_e32 v3, 0xffff0000, v4
	v_lshlrev_b32_e32 v4, 16, v5
	v_and_b32_e32 v5, 0xffff0000, v5
	v_lshlrev_b32_e32 v6, 16, v14
	v_and_b32_e32 v7, 0xffff0000, v14
	v_lshlrev_b32_e32 v8, 16, v15
	v_and_b32_e32 v9, 0xffff0000, v15
	v_lshlrev_b32_e32 v14, 16, v16
	v_and_b32_e32 v15, 0xffff0000, v16
	v_lshlrev_b32_e32 v16, 16, v17
	v_and_b32_e32 v17, 0xffff0000, v17
	s_cselect_b64 s[18:19], -1, 0
	v_lshl_add_u64 v[146:147], v[180:181], 0, s[30:31]
	s_mov_b32 s50, 0
	v_add_u32_e32 v157, 0, v162
	v_lshlrev_b32_e32 v180, 1, v161
	s_barrier
	s_branch .LBB0_2230

.LBB0_2279:
	s_waitcnt vmcnt(0)
	v_lshlrev_b32_e32 v106, 16, v50
	v_and_b32_e32 v107, 0xffff0000, v50
	v_lshlrev_b32_e32 v108, 16, v51
	v_and_b32_e32 v109, 0xffff0000, v51
	v_lshlrev_b32_e32 v110, 16, v52
	v_and_b32_e32 v111, 0xffff0000, v52
	v_lshlrev_b32_e32 v112, 16, v53
	v_and_b32_e32 v113, 0xffff0000, v53
	v_lshlrev_b32_e32 v50, 16, v12
	v_and_b32_e32 v51, 0xffff0000, v12
	v_lshlrev_b32_e32 v52, 16, v13
	v_and_b32_e32 v53, 0xffff0000, v13
	s_add_i32 m0, s56, 0x18000
	v_lshl_add_u64 v[12:13], v[80:81], 0, s[16:17]
	s_lshl_b32 s25, s22, 13
	s_lshl_b32 s26, s55, 7
	global_load_lds_dwordx4 v[12:13], off
	v_lshl_add_u64 v[12:13], v[78:79], 0, s[16:17]
	s_add_i32 m0, s56, 0x1a000
	s_add_i32 s60, s56, 0x8000
	s_add_i32 s61, s56, 0xa000
	global_load_lds_dwordx4 v[12:13], off
	v_lshl_add_u64 v[12:13], v[66:67], 0, s[16:17]
	s_mov_b32 m0, s60
	s_add_u32 s22, s30, 0x158080
	global_load_lds_dwordx4 v[12:13], off
	v_lshl_add_u64 v[12:13], v[68:69], 0, s[16:17]
	s_mov_b32 m0, s61
	s_addc_u32 s23, s31, 0
	global_load_lds_dwordx4 v[12:13], off
	s_add_i32 m0, s56, 0x1c000
	v_lshl_add_u64 v[12:13], s[22:23], 0, v[150:151]
	global_load_lds_dwordx4 v[12:13], off
	v_lshl_add_u64 v[12:13], s[22:23], 0, v[154:155]
	s_add_i32 m0, s56, 0x1e000
	s_mov_b64 s[22:23], 0x94000
	global_load_lds_dwordx4 v[12:13], off
	s_waitcnt vmcnt(8)
	s_barrier
	v_lshl_add_u64 v[156:157], v[130:131], 0, s[22:23]
	s_mov_b64 s[22:23], 0x9000
	v_or_b32_e32 v199, s54, v197
	v_lshl_add_u64 v[158:159], v[130:131], 0, s[22:23]
	v_lshlrev_b32_e32 v130, 6, v199
	s_movk_i32 s22, 0x3c0
	v_lshlrev_b32_e32 v131, 2, v199
	v_and_or_b32 v130, v130, s22, v180
	v_and_b32_e32 v131, 32, v131
	v_bitop3_b32 v141, v130, s25, v131 bitop3:0xde
	v_lshlrev_b32_e32 v131, 2, v197
	v_lshl_or_b32 v130, v197, 6, v180
	v_and_b32_e32 v131, 32, v131
	v_bitop3_b32 v200, v130, s26, v131 bitop3:0xde
	s_movk_i32 s26, 0x1580
	v_lshrrev_b32_e32 v131, 1, v132
	v_mul_lo_u32 v130, v134, s26
	s_mov_b32 s27, 0x15800
	s_cmpk_lt_u32 s24, 0x100
	v_mad_u64_u32 v[130:131], s[24:25], v131, s27, v[130:131]
	v_or_b32_e32 v130, v130, v133
	v_add_lshl_u32 v180, v130, v135, 1
	v_lshrrev_b32_e32 v131, 1, v136
	v_mul_lo_u32 v130, v138, s26
	v_mad_u64_u32 v[130:131], s[24:25], v131, s27, v[130:131]
	s_waitcnt vmcnt(6)
	s_mov_b64 s[34:35], 0x158080
	v_or_b32_e32 v130, v130, v137
	v_lshlrev_b32_e32 v140, 3, v198
	v_lshl_add_u64 v[160:161], v[180:181], 0, s[34:35]
	v_add_lshl_u32 v180, v130, v139, 1
	v_lshlrev_b32_e32 v118, 16, v62
	v_and_b32_e32 v119, 0xffff0000, v62
	v_lshlrev_b32_e32 v120, 16, v63
	v_and_b32_e32 v121, 0xffff0000, v63
	v_lshlrev_b32_e32 v114, 16, v64
	v_and_b32_e32 v115, 0xffff0000, v64
	v_lshlrev_b32_e32 v116, 16, v65
	v_and_b32_e32 v117, 0xffff0000, v65
	v_lshlrev_b32_e32 v126, 16, v58
	v_and_b32_e32 v127, 0xffff0000, v58
	v_lshlrev_b32_e32 v128, 16, v59
	v_and_b32_e32 v129, 0xffff0000, v59
	v_lshlrev_b32_e32 v122, 16, v60
	v_and_b32_e32 v123, 0xffff0000, v60
	v_lshlrev_b32_e32 v124, 16, v61
	v_and_b32_e32 v125, 0xffff0000, v61
	v_lshlrev_b32_e32 v98, 16, v54
	v_and_b32_e32 v99, 0xffff0000, v54
	v_lshlrev_b32_e32 v100, 16, v55
	v_and_b32_e32 v101, 0xffff0000, v55
	v_lshlrev_b32_e32 v102, 16, v56
	v_and_b32_e32 v103, 0xffff0000, v56
	v_lshlrev_b32_e32 v104, 16, v57
	v_and_b32_e32 v105, 0xffff0000, v57
	v_lshlrev_b32_e32 v70, 16, v46
	v_and_b32_e32 v71, 0xffff0000, v46
	v_lshlrev_b32_e32 v72, 16, v47
	v_and_b32_e32 v73, 0xffff0000, v47
	v_lshlrev_b32_e32 v74, 16, v48
	v_and_b32_e32 v75, 0xffff0000, v48
	v_lshlrev_b32_e32 v76, 16, v49
	v_and_b32_e32 v77, 0xffff0000, v49
	v_lshlrev_b32_e32 v82, 16, v30
	v_and_b32_e32 v83, 0xffff0000, v30
	v_lshlrev_b32_e32 v84, 16, v31
	v_and_b32_e32 v85, 0xffff0000, v31
	v_lshlrev_b32_e32 v86, 16, v32
	v_and_b32_e32 v87, 0xffff0000, v32
	v_lshlrev_b32_e32 v88, 16, v33
	v_and_b32_e32 v89, 0xffff0000, v33
	v_lshlrev_b32_e32 v30, 16, v34
	v_and_b32_e32 v31, 0xffff0000, v34
	v_lshlrev_b32_e32 v32, 16, v35
	v_and_b32_e32 v33, 0xffff0000, v35
	v_lshlrev_b32_e32 v34, 16, v36
	v_and_b32_e32 v35, 0xffff0000, v36
	v_lshlrev_b32_e32 v36, 16, v37
	v_and_b32_e32 v37, 0xffff0000, v37
	v_lshlrev_b32_e32 v54, 16, v22
	v_and_b32_e32 v55, 0xffff0000, v22
	v_lshlrev_b32_e32 v56, 16, v23
	v_and_b32_e32 v57, 0xffff0000, v23
	v_lshlrev_b32_e32 v58, 16, v24
	v_and_b32_e32 v59, 0xffff0000, v24
	v_lshlrev_b32_e32 v60, 16, v25
	v_and_b32_e32 v61, 0xffff0000, v25
	v_lshlrev_b32_e32 v22, 16, v26
	v_and_b32_e32 v23, 0xffff0000, v26
	v_lshlrev_b32_e32 v24, 16, v27
	v_and_b32_e32 v25, 0xffff0000, v27
	v_lshlrev_b32_e32 v26, 16, v28
	v_and_b32_e32 v27, 0xffff0000, v28
	v_lshlrev_b32_e32 v28, 16, v29
	v_and_b32_e32 v29, 0xffff0000, v29
	v_lshlrev_b32_e32 v46, 16, v10
	v_and_b32_e32 v47, 0xffff0000, v10
	v_lshlrev_b32_e32 v48, 16, v11
	v_and_b32_e32 v49, 0xffff0000, v11
	v_lshlrev_b32_e32 v10, 16, v42
	v_and_b32_e32 v11, 0xffff0000, v42
	v_lshlrev_b32_e32 v12, 16, v43
	v_and_b32_e32 v13, 0xffff0000, v43
	v_lshlrev_b32_e32 v78, 16, v44
	v_and_b32_e32 v79, 0xffff0000, v44
	v_lshlrev_b32_e32 v80, 16, v45
	v_and_b32_e32 v81, 0xffff0000, v45
	v_lshlrev_b32_e32 v90, 16, v38
	v_and_b32_e32 v91, 0xffff0000, v38
	v_lshlrev_b32_e32 v92, 16, v39
	v_and_b32_e32 v93, 0xffff0000, v39
	v_lshlrev_b32_e32 v94, 16, v40
	v_and_b32_e32 v95, 0xffff0000, v40
	v_lshlrev_b32_e32 v96, 16, v41
	v_and_b32_e32 v97, 0xffff0000, v41
	v_lshlrev_b32_e32 v38, 16, v14
	v_and_b32_e32 v39, 0xffff0000, v14
	v_lshlrev_b32_e32 v40, 16, v15
	v_and_b32_e32 v41, 0xffff0000, v15
	v_lshlrev_b32_e32 v42, 16, v16
	v_and_b32_e32 v43, 0xffff0000, v16
	v_lshlrev_b32_e32 v44, 16, v17
	v_and_b32_e32 v45, 0xffff0000, v17
	v_lshlrev_b32_e32 v62, 16, v2
	v_and_b32_e32 v63, 0xffff0000, v2
	v_lshlrev_b32_e32 v64, 16, v3
	v_and_b32_e32 v65, 0xffff0000, v3
	v_lshlrev_b32_e32 v66, 16, v4
	v_and_b32_e32 v67, 0xffff0000, v4
	v_lshlrev_b32_e32 v68, 16, v5
	v_and_b32_e32 v69, 0xffff0000, v5
	v_lshlrev_b32_e32 v2, 16, v6
	v_and_b32_e32 v3, 0xffff0000, v6
	v_lshlrev_b32_e32 v4, 16, v7
	v_and_b32_e32 v5, 0xffff0000, v7
	v_lshlrev_b32_e32 v6, 16, v8
	v_and_b32_e32 v7, 0xffff0000, v8
	v_lshlrev_b32_e32 v8, 16, v9
	v_and_b32_e32 v9, 0xffff0000, v9
	v_lshlrev_b32_e32 v14, 16, v18
	v_and_b32_e32 v15, 0xffff0000, v18
	v_lshlrev_b32_e32 v16, 16, v19
	v_and_b32_e32 v17, 0xffff0000, v19
	v_lshlrev_b32_e32 v18, 16, v20
	v_and_b32_e32 v19, 0xffff0000, v20
	v_lshlrev_b32_e32 v20, 16, v21
	v_and_b32_e32 v21, 0xffff0000, v21
	s_cselect_b64 s[22:23], -1, 0
	v_lshl_add_u64 v[162:163], v[180:181], 0, s[34:35]
	s_mov_b32 s62, 0
	v_add_u32_e32 v201, 0, v141
	v_lshlrev_b32_e32 v180, 1, v140
	s_barrier
	s_branch .LBB0_2282
